# rwkv prep v-rows tile loop: 32 loads in flight per half tile
# speedup vs baseline: 1.0462x; 1.0089x over previous
; template <class Fn>
; __device__ __forceinline__ void prep_mat(bf16_t* dst, int NR, int KC, int ldd, const Fn f, int& gw, int NGW, LAS float* scr, int lane) {
;     ...
; #pragma unroll 4
;         for (int i = 0; i < 32; ++i) { const int kk = 2 * i + (lane >> 5); scr[kk * 33 + (lane & 31)] = f(n0 + (lane & 31), k0 + kk); }
; __device__ __forceinline__ void prep_rwkv(const LAS unsigned* PL, int idx, bf16_t* WR2, bf16_t* WR3, bf16_t* WG, bf16_t* WO, int gw, int NGW, LAS float* scr, int lane) {
;     ...
;             prep_mat(WR2 + (size_t)2048 * 1024, 1024, 2048, 2048, [=](int n, int kk) -> float {
;                 const int k = kk & 1023, hi = kk >> 10;
;                 const float m = mu[3 * D + k];
;                 return w_v[(size_t)k * D + n] * (hi ? m : 1.f - m); }, gw, NGW, scr, lane);
.LBB0_620:
	v_add_u32_e32 v194, 0, v9
	v_and_b32_e32 v195, 0x3ff, v194
	v_lshl_add_u32 v2, v195, 2, s24
	global_load_dword v156, v2, s[12:13]
	v_lshlrev_b32_e32 v2, 12, v195
	v_lshl_add_u64 v[198:199], v[6:7], 0, v[2:3]
	global_load_dword v172, v[198:199], off
	v_add_u32_e32 v194, 2, v9
	v_and_b32_e32 v195, 0x3ff, v194
	v_lshl_add_u32 v2, v195, 2, s24
	global_load_dword v157, v2, s[12:13]
	v_lshlrev_b32_e32 v2, 12, v195
	v_lshl_add_u64 v[198:199], v[6:7], 0, v[2:3]
	global_load_dword v173, v[198:199], off
	v_add_u32_e32 v194, 4, v9
	v_and_b32_e32 v195, 0x3ff, v194
	v_lshl_add_u32 v2, v195, 2, s24
	global_load_dword v158, v2, s[12:13]
	v_lshlrev_b32_e32 v2, 12, v195
	v_lshl_add_u64 v[198:199], v[6:7], 0, v[2:3]
	global_load_dword v174, v[198:199], off
	v_add_u32_e32 v194, 6, v9
	v_and_b32_e32 v195, 0x3ff, v194
	v_lshl_add_u32 v2, v195, 2, s24
	global_load_dword v159, v2, s[12:13]
	v_lshlrev_b32_e32 v2, 12, v195
	v_lshl_add_u64 v[198:199], v[6:7], 0, v[2:3]
	global_load_dword v175, v[198:199], off
	v_add_u32_e32 v194, 8, v9
	v_and_b32_e32 v195, 0x3ff, v194
	v_lshl_add_u32 v2, v195, 2, s24
	global_load_dword v160, v2, s[12:13]
	v_lshlrev_b32_e32 v2, 12, v195
	v_lshl_add_u64 v[198:199], v[6:7], 0, v[2:3]
	global_load_dword v182, v[198:199], off
	v_add_u32_e32 v194, 10, v9
	v_and_b32_e32 v195, 0x3ff, v194
	v_lshl_add_u32 v2, v195, 2, s24
	global_load_dword v161, v2, s[12:13]
	v_lshlrev_b32_e32 v2, 12, v195
	v_lshl_add_u64 v[198:199], v[6:7], 0, v[2:3]
	global_load_dword v183, v[198:199], off
	v_add_u32_e32 v194, 12, v9
	v_and_b32_e32 v195, 0x3ff, v194
	v_lshl_add_u32 v2, v195, 2, s24
	global_load_dword v162, v2, s[12:13]
	v_lshlrev_b32_e32 v2, 12, v195
	v_lshl_add_u64 v[198:199], v[6:7], 0, v[2:3]
	global_load_dword v184, v[198:199], off
	v_add_u32_e32 v194, 14, v9
	v_and_b32_e32 v195, 0x3ff, v194
	v_lshl_add_u32 v2, v195, 2, s24
	global_load_dword v163, v2, s[12:13]
	v_lshlrev_b32_e32 v2, 12, v195
	v_lshl_add_u64 v[198:199], v[6:7], 0, v[2:3]
	global_load_dword v185, v[198:199], off
	v_add_u32_e32 v194, 16, v9
	v_and_b32_e32 v195, 0x3ff, v194
	v_lshl_add_u32 v2, v195, 2, s24
	global_load_dword v164, v2, s[12:13]
	v_lshlrev_b32_e32 v2, 12, v195
	v_lshl_add_u64 v[198:199], v[6:7], 0, v[2:3]
	global_load_dword v186, v[198:199], off
	v_add_u32_e32 v194, 18, v9
	v_and_b32_e32 v195, 0x3ff, v194
	v_lshl_add_u32 v2, v195, 2, s24
	global_load_dword v165, v2, s[12:13]
	v_lshlrev_b32_e32 v2, 12, v195
	v_lshl_add_u64 v[198:199], v[6:7], 0, v[2:3]
	global_load_dword v187, v[198:199], off
	v_add_u32_e32 v194, 20, v9
	v_and_b32_e32 v195, 0x3ff, v194
	v_lshl_add_u32 v2, v195, 2, s24
	global_load_dword v166, v2, s[12:13]
	v_lshlrev_b32_e32 v2, 12, v195
	v_lshl_add_u64 v[198:199], v[6:7], 0, v[2:3]
	global_load_dword v188, v[198:199], off
	v_add_u32_e32 v194, 22, v9
	v_and_b32_e32 v195, 0x3ff, v194
	v_lshl_add_u32 v2, v195, 2, s24
	global_load_dword v167, v2, s[12:13]
	v_lshlrev_b32_e32 v2, 12, v195
	v_lshl_add_u64 v[198:199], v[6:7], 0, v[2:3]
	global_load_dword v189, v[198:199], off
	v_add_u32_e32 v194, 24, v9
	v_and_b32_e32 v195, 0x3ff, v194
	v_lshl_add_u32 v2, v195, 2, s24
	global_load_dword v168, v2, s[12:13]
	v_lshlrev_b32_e32 v2, 12, v195
	v_lshl_add_u64 v[198:199], v[6:7], 0, v[2:3]
	global_load_dword v190, v[198:199], off
	v_add_u32_e32 v194, 26, v9
	v_and_b32_e32 v195, 0x3ff, v194
	v_lshl_add_u32 v2, v195, 2, s24
	global_load_dword v169, v2, s[12:13]
	v_lshlrev_b32_e32 v2, 12, v195
	v_lshl_add_u64 v[198:199], v[6:7], 0, v[2:3]
	global_load_dword v191, v[198:199], off
	v_add_u32_e32 v194, 28, v9
	v_and_b32_e32 v195, 0x3ff, v194
	v_lshl_add_u32 v2, v195, 2, s24
	global_load_dword v170, v2, s[12:13]
	v_lshlrev_b32_e32 v2, 12, v195
	v_lshl_add_u64 v[198:199], v[6:7], 0, v[2:3]
	global_load_dword v192, v[198:199], off
	v_add_u32_e32 v194, 30, v9
	v_and_b32_e32 v195, 0x3ff, v194
	v_lshl_add_u32 v2, v195, 2, s24
	global_load_dword v171, v2, s[12:13]
	v_lshlrev_b32_e32 v2, 12, v195
	v_lshl_add_u64 v[198:199], v[6:7], 0, v[2:3]
	global_load_dword v193, v[198:199], off
	s_waitcnt vmcnt(30)
	v_add_u32_e32 v194, 0, v9
	v_cmp_gt_u32_e32 vcc, s25, v194
	v_sub_f32_e32 v196, 1.0, v156
	s_nop 0
	v_cndmask_b32_e32 v196, v156, v196, vcc
	v_mul_f32_e32 v196, v172, v196
	ds_write_b32 v10, v196
	s_waitcnt vmcnt(28)
	v_add_u32_e32 v194, 2, v9
	v_cmp_gt_u32_e32 vcc, s25, v194
	v_sub_f32_e32 v196, 1.0, v157
	s_nop 0
	v_cndmask_b32_e32 v196, v157, v196, vcc
	v_mul_f32_e32 v196, v173, v196
	ds_write_b32 v10, v196 offset:264
	s_waitcnt vmcnt(26)
	v_add_u32_e32 v194, 4, v9
	v_cmp_gt_u32_e32 vcc, s25, v194
	v_sub_f32_e32 v196, 1.0, v158
	s_nop 0
	v_cndmask_b32_e32 v196, v158, v196, vcc
	v_mul_f32_e32 v196, v174, v196
	ds_write_b32 v10, v196 offset:528
	s_waitcnt vmcnt(24)
	v_add_u32_e32 v194, 6, v9
	v_cmp_gt_u32_e32 vcc, s25, v194
	v_sub_f32_e32 v196, 1.0, v159
	s_nop 0
	v_cndmask_b32_e32 v196, v159, v196, vcc
	v_mul_f32_e32 v196, v175, v196
	ds_write_b32 v10, v196 offset:792
	s_waitcnt vmcnt(22)
	v_add_u32_e32 v194, 8, v9
	v_cmp_gt_u32_e32 vcc, s25, v194
	v_sub_f32_e32 v196, 1.0, v160
	s_nop 0
	v_cndmask_b32_e32 v196, v160, v196, vcc
	v_mul_f32_e32 v196, v182, v196
	ds_write_b32 v10, v196 offset:1056
	s_waitcnt vmcnt(20)
	v_add_u32_e32 v194, 10, v9
	v_cmp_gt_u32_e32 vcc, s25, v194
	v_sub_f32_e32 v196, 1.0, v161
	s_nop 0
	v_cndmask_b32_e32 v196, v161, v196, vcc
	v_mul_f32_e32 v196, v183, v196
	ds_write_b32 v10, v196 offset:1320
	s_waitcnt vmcnt(18)
	v_add_u32_e32 v194, 12, v9
	v_cmp_gt_u32_e32 vcc, s25, v194
	v_sub_f32_e32 v196, 1.0, v162
	s_nop 0
	v_cndmask_b32_e32 v196, v162, v196, vcc
	v_mul_f32_e32 v196, v184, v196
	ds_write_b32 v10, v196 offset:1584
	s_waitcnt vmcnt(16)
; template <class Fn>
; __device__ __forceinline__ void prep_mat(bf16_t* dst, int NR, int KC, int ldd, const Fn f, int& gw, int NGW, LAS float* scr, int lane) {
;     ...
; #pragma unroll 4
;         for (int i = 0; i < 32; ++i) { const int kk = 2 * i + (lane >> 5); scr[kk * 33 + (lane & 31)] = f(n0 + (lane & 31), k0 + kk); }
; __device__ __forceinline__ void prep_rwkv(const LAS unsigned* PL, int idx, bf16_t* WR2, bf16_t* WR3, bf16_t* WG, bf16_t* WO, int gw, int NGW, LAS float* scr, int lane) {
;     ...
;             prep_mat(WR2 + (size_t)2048 * 1024, 1024, 2048, 2048, [=](int n, int kk) -> float {
;                 const int k = kk & 1023, hi = kk >> 10;
;                 const float m = mu[3 * D + k];
;                 return w_v[(size_t)k * D + n] * (hi ? m : 1.f - m); }, gw, NGW, scr, lane);
	v_add_u32_e32 v194, 14, v9
	v_cmp_gt_u32_e32 vcc, s25, v194
	v_sub_f32_e32 v196, 1.0, v163
	s_nop 0
	v_cndmask_b32_e32 v196, v163, v196, vcc
	v_mul_f32_e32 v196, v185, v196
	ds_write_b32 v10, v196 offset:1848
	s_waitcnt vmcnt(14)
	v_add_u32_e32 v194, 16, v9
	v_cmp_gt_u32_e32 vcc, s25, v194
	v_sub_f32_e32 v196, 1.0, v164
	s_nop 0
	v_cndmask_b32_e32 v196, v164, v196, vcc
	v_mul_f32_e32 v196, v186, v196
	ds_write_b32 v10, v196 offset:2112
	s_waitcnt vmcnt(12)
	v_add_u32_e32 v194, 18, v9
	v_cmp_gt_u32_e32 vcc, s25, v194
	v_sub_f32_e32 v196, 1.0, v165
	s_nop 0
	v_cndmask_b32_e32 v196, v165, v196, vcc
	v_mul_f32_e32 v196, v187, v196
	ds_write_b32 v10, v196 offset:2376
	s_waitcnt vmcnt(10)
	v_add_u32_e32 v194, 20, v9
	v_cmp_gt_u32_e32 vcc, s25, v194
	v_sub_f32_e32 v196, 1.0, v166
	s_nop 0
	v_cndmask_b32_e32 v196, v166, v196, vcc
	v_mul_f32_e32 v196, v188, v196
	ds_write_b32 v10, v196 offset:2640
	s_waitcnt vmcnt(8)
	v_add_u32_e32 v194, 22, v9
	v_cmp_gt_u32_e32 vcc, s25, v194
	v_sub_f32_e32 v196, 1.0, v167
	s_nop 0
	v_cndmask_b32_e32 v196, v167, v196, vcc
	v_mul_f32_e32 v196, v189, v196
	ds_write_b32 v10, v196 offset:2904
	s_waitcnt vmcnt(6)
	v_add_u32_e32 v194, 24, v9
	v_cmp_gt_u32_e32 vcc, s25, v194
	v_sub_f32_e32 v196, 1.0, v168
	s_nop 0
	v_cndmask_b32_e32 v196, v168, v196, vcc
	v_mul_f32_e32 v196, v190, v196
	ds_write_b32 v10, v196 offset:3168
	s_waitcnt vmcnt(4)
	v_add_u32_e32 v194, 26, v9
	v_cmp_gt_u32_e32 vcc, s25, v194
	v_sub_f32_e32 v196, 1.0, v169
	s_nop 0
	v_cndmask_b32_e32 v196, v169, v196, vcc
	v_mul_f32_e32 v196, v191, v196
	ds_write_b32 v10, v196 offset:3432
	s_waitcnt vmcnt(2)
	v_add_u32_e32 v194, 28, v9
	v_cmp_gt_u32_e32 vcc, s25, v194
	v_sub_f32_e32 v196, 1.0, v170
	s_nop 0
	v_cndmask_b32_e32 v196, v170, v196, vcc
	v_mul_f32_e32 v196, v192, v196
	ds_write_b32 v10, v196 offset:3696
	s_waitcnt vmcnt(0)
	v_add_u32_e32 v194, 30, v9
	v_cmp_gt_u32_e32 vcc, s25, v194
	v_sub_f32_e32 v196, 1.0, v171
	s_nop 0
	v_cndmask_b32_e32 v196, v171, v196, vcc
	v_mul_f32_e32 v196, v193, v196
	ds_write_b32 v10, v196 offset:3960
	v_add_u32_e32 v194, 32, v9
	v_and_b32_e32 v195, 0x3ff, v194
	v_lshl_add_u32 v2, v195, 2, s24
	global_load_dword v156, v2, s[12:13]
	v_lshlrev_b32_e32 v2, 12, v195
	v_lshl_add_u64 v[198:199], v[6:7], 0, v[2:3]
	global_load_dword v172, v[198:199], off
	v_add_u32_e32 v194, 34, v9
	v_and_b32_e32 v195, 0x3ff, v194
	v_lshl_add_u32 v2, v195, 2, s24
	global_load_dword v157, v2, s[12:13]
	v_lshlrev_b32_e32 v2, 12, v195
	v_lshl_add_u64 v[198:199], v[6:7], 0, v[2:3]
	global_load_dword v173, v[198:199], off
	v_add_u32_e32 v194, 36, v9
	v_and_b32_e32 v195, 0x3ff, v194
	v_lshl_add_u32 v2, v195, 2, s24
	global_load_dword v158, v2, s[12:13]
	v_lshlrev_b32_e32 v2, 12, v195
	v_lshl_add_u64 v[198:199], v[6:7], 0, v[2:3]
	global_load_dword v174, v[198:199], off
	v_add_u32_e32 v194, 38, v9
	v_and_b32_e32 v195, 0x3ff, v194
	v_lshl_add_u32 v2, v195, 2, s24
	global_load_dword v159, v2, s[12:13]
	v_lshlrev_b32_e32 v2, 12, v195
	v_lshl_add_u64 v[198:199], v[6:7], 0, v[2:3]
	global_load_dword v175, v[198:199], off
	v_add_u32_e32 v194, 40, v9
	v_and_b32_e32 v195, 0x3ff, v194
	v_lshl_add_u32 v2, v195, 2, s24
	global_load_dword v160, v2, s[12:13]
	v_lshlrev_b32_e32 v2, 12, v195
	v_lshl_add_u64 v[198:199], v[6:7], 0, v[2:3]
	global_load_dword v182, v[198:199], off
	v_add_u32_e32 v194, 42, v9
	v_and_b32_e32 v195, 0x3ff, v194
	v_lshl_add_u32 v2, v195, 2, s24
	global_load_dword v161, v2, s[12:13]
	v_lshlrev_b32_e32 v2, 12, v195
	v_lshl_add_u64 v[198:199], v[6:7], 0, v[2:3]
	global_load_dword v183, v[198:199], off
	v_add_u32_e32 v194, 44, v9
	v_and_b32_e32 v195, 0x3ff, v194
	v_lshl_add_u32 v2, v195, 2, s24
	global_load_dword v162, v2, s[12:13]
	v_lshlrev_b32_e32 v2, 12, v195
	v_lshl_add_u64 v[198:199], v[6:7], 0, v[2:3]
	global_load_dword v184, v[198:199], off
	v_add_u32_e32 v194, 46, v9
	v_and_b32_e32 v195, 0x3ff, v194
	v_lshl_add_u32 v2, v195, 2, s24
	global_load_dword v163, v2, s[12:13]
	v_lshlrev_b32_e32 v2, 12, v195
	v_lshl_add_u64 v[198:199], v[6:7], 0, v[2:3]
	global_load_dword v185, v[198:199], off
	v_add_u32_e32 v194, 48, v9
	v_and_b32_e32 v195, 0x3ff, v194
	v_lshl_add_u32 v2, v195, 2, s24
	global_load_dword v164, v2, s[12:13]
	v_lshlrev_b32_e32 v2, 12, v195
	v_lshl_add_u64 v[198:199], v[6:7], 0, v[2:3]
	global_load_dword v186, v[198:199], off
	v_add_u32_e32 v194, 50, v9
	v_and_b32_e32 v195, 0x3ff, v194
	v_lshl_add_u32 v2, v195, 2, s24
	global_load_dword v165, v2, s[12:13]
	v_lshlrev_b32_e32 v2, 12, v195
	v_lshl_add_u64 v[198:199], v[6:7], 0, v[2:3]
	global_load_dword v187, v[198:199], off
	v_add_u32_e32 v194, 52, v9
	v_and_b32_e32 v195, 0x3ff, v194
	v_lshl_add_u32 v2, v195, 2, s24
	global_load_dword v166, v2, s[12:13]
	v_lshlrev_b32_e32 v2, 12, v195
	v_lshl_add_u64 v[198:199], v[6:7], 0, v[2:3]
	global_load_dword v188, v[198:199], off
	v_add_u32_e32 v194, 54, v9
	v_and_b32_e32 v195, 0x3ff, v194
	v_lshl_add_u32 v2, v195, 2, s24
	global_load_dword v167, v2, s[12:13]
	v_lshlrev_b32_e32 v2, 12, v195
	v_lshl_add_u64 v[198:199], v[6:7], 0, v[2:3]
	global_load_dword v189, v[198:199], off
	v_add_u32_e32 v194, 56, v9
	v_and_b32_e32 v195, 0x3ff, v194
	v_lshl_add_u32 v2, v195, 2, s24
	global_load_dword v168, v2, s[12:13]
	v_lshlrev_b32_e32 v2, 12, v195
	v_lshl_add_u64 v[198:199], v[6:7], 0, v[2:3]
	global_load_dword v190, v[198:199], off
	v_add_u32_e32 v194, 58, v9
	v_and_b32_e32 v195, 0x3ff, v194
	v_lshl_add_u32 v2, v195, 2, s24
	global_load_dword v169, v2, s[12:13]
	v_lshlrev_b32_e32 v2, 12, v195
	v_lshl_add_u64 v[198:199], v[6:7], 0, v[2:3]
	global_load_dword v191, v[198:199], off
	v_add_u32_e32 v194, 60, v9
	v_and_b32_e32 v195, 0x3ff, v194
	v_lshl_add_u32 v2, v195, 2, s24
	global_load_dword v170, v2, s[12:13]
	v_lshlrev_b32_e32 v2, 12, v195
	v_lshl_add_u64 v[198:199], v[6:7], 0, v[2:3]
	global_load_dword v192, v[198:199], off
	v_add_u32_e32 v194, 62, v9
	v_and_b32_e32 v195, 0x3ff, v194
	v_lshl_add_u32 v2, v195, 2, s24
	global_load_dword v171, v2, s[12:13]
	v_lshlrev_b32_e32 v2, 12, v195
	v_lshl_add_u64 v[198:199], v[6:7], 0, v[2:3]
	global_load_dword v193, v[198:199], off
	s_waitcnt vmcnt(30)
; #define LAS __attribute__((address_space(3)))
; #define GAS __attribute__((address_space(1)))
; __device__ __forceinline__ unsigned cvt_pk_bf16(float lo, float hi) { const f32x2 v = {lo, hi}; return __builtin_bit_cast(unsigned, __builtin_convertvector(v, b16x2_t)); }
; #define LDS_WAIT() asm volatile("s_waitcnt lgkmcnt(0)" ::: "memory")
; template <class Fn>
; __device__ __forceinline__ void prep_mat(bf16_t* dst, int NR, int KC, int ldd, const Fn f, int& gw, int NGW, LAS float* scr, int lane) {
;     ...
; #pragma unroll 4
;         for (int i = 0; i < 32; ++i) { const int kk = 2 * i + (lane >> 5); scr[kk * 33 + (lane & 31)] = f(n0 + (lane & 31), k0 + kk); }
;         LDS_WAIT(); asm volatile("" ::: "memory");
;         const int c = lane & 7;
; #pragma unroll
;         for (int j = 0; j < 4; ++j) { const int n = (lane >> 3) + 8 * j; const LAS float* s = scr + (8 * c) * 33 + n;
;             u32x4 o; o.x = cvt_pk_bf16(s[0 * 33], s[1 * 33]); o.y = cvt_pk_bf16(s[2 * 33], s[3 * 33]); o.z = cvt_pk_bf16(s[4 * 33], s[5 * 33]); o.w = cvt_pk_bf16(s[6 * 33], s[7 * 33]);
;             *(GAS u32x4*)(dst + (size_t)(n0 + n) * ldd + k0 + 8 * c) = o; }
;         LDS_WAIT(); asm volatile("" ::: "memory");
;     }
; __device__ __forceinline__ void prep_rwkv(const LAS unsigned* PL, int idx, bf16_t* WR2, bf16_t* WR3, bf16_t* WG, bf16_t* WO, int gw, int NGW, LAS float* scr, int lane) {
;     ...
;             prep_mat(WR2 + (size_t)2048 * 1024, 1024, 2048, 2048, [=](int n, int kk) -> float {
;                 const int k = kk & 1023, hi = kk >> 10;
;                 const float m = mu[3 * D + k];
;                 return w_v[(size_t)k * D + n] * (hi ? m : 1.f - m); }, gw, NGW, scr, lane);
	v_add_u32_e32 v194, 32, v9
	v_cmp_gt_u32_e32 vcc, s25, v194
	v_sub_f32_e32 v196, 1.0, v156
	s_nop 0
	v_cndmask_b32_e32 v196, v156, v196, vcc
	v_mul_f32_e32 v196, v172, v196
	ds_write_b32 v10, v196 offset:4224
	s_waitcnt vmcnt(28)
	v_add_u32_e32 v194, 34, v9
	v_cmp_gt_u32_e32 vcc, s25, v194
	v_sub_f32_e32 v196, 1.0, v157
	s_nop 0
	v_cndmask_b32_e32 v196, v157, v196, vcc
	v_mul_f32_e32 v196, v173, v196
	ds_write_b32 v10, v196 offset:4488
	s_waitcnt vmcnt(26)
	v_add_u32_e32 v194, 36, v9
	v_cmp_gt_u32_e32 vcc, s25, v194
	v_sub_f32_e32 v196, 1.0, v158
	s_nop 0
	v_cndmask_b32_e32 v196, v158, v196, vcc
	v_mul_f32_e32 v196, v174, v196
	ds_write_b32 v10, v196 offset:4752
	s_waitcnt vmcnt(24)
	v_add_u32_e32 v194, 38, v9
	v_cmp_gt_u32_e32 vcc, s25, v194
	v_sub_f32_e32 v196, 1.0, v159
	s_nop 0
	v_cndmask_b32_e32 v196, v159, v196, vcc
	v_mul_f32_e32 v196, v175, v196
	ds_write_b32 v10, v196 offset:5016
	s_waitcnt vmcnt(22)
	v_add_u32_e32 v194, 40, v9
	v_cmp_gt_u32_e32 vcc, s25, v194
	v_sub_f32_e32 v196, 1.0, v160
	s_nop 0
	v_cndmask_b32_e32 v196, v160, v196, vcc
	v_mul_f32_e32 v196, v182, v196
	ds_write_b32 v10, v196 offset:5280
	s_waitcnt vmcnt(20)
	v_add_u32_e32 v194, 42, v9
	v_cmp_gt_u32_e32 vcc, s25, v194
	v_sub_f32_e32 v196, 1.0, v161
	s_nop 0
	v_cndmask_b32_e32 v196, v161, v196, vcc
	v_mul_f32_e32 v196, v183, v196
	ds_write_b32 v10, v196 offset:5544
	s_waitcnt vmcnt(18)
	v_add_u32_e32 v194, 44, v9
	v_cmp_gt_u32_e32 vcc, s25, v194
	v_sub_f32_e32 v196, 1.0, v162
	s_nop 0
	v_cndmask_b32_e32 v196, v162, v196, vcc
	v_mul_f32_e32 v196, v184, v196
	ds_write_b32 v10, v196 offset:5808
	s_waitcnt vmcnt(16)
	v_add_u32_e32 v194, 46, v9
	v_cmp_gt_u32_e32 vcc, s25, v194
	v_sub_f32_e32 v196, 1.0, v163
	s_nop 0
	v_cndmask_b32_e32 v196, v163, v196, vcc
	v_mul_f32_e32 v196, v185, v196
	ds_write_b32 v10, v196 offset:6072
	s_waitcnt vmcnt(14)
	v_add_u32_e32 v194, 48, v9
	v_cmp_gt_u32_e32 vcc, s25, v194
	v_sub_f32_e32 v196, 1.0, v164
	s_nop 0
	v_cndmask_b32_e32 v196, v164, v196, vcc
	v_mul_f32_e32 v196, v186, v196
	ds_write_b32 v10, v196 offset:6336
	s_waitcnt vmcnt(12)
	v_add_u32_e32 v194, 50, v9
	v_cmp_gt_u32_e32 vcc, s25, v194
	v_sub_f32_e32 v196, 1.0, v165
	s_nop 0
	v_cndmask_b32_e32 v196, v165, v196, vcc
	v_mul_f32_e32 v196, v187, v196
	ds_write_b32 v10, v196 offset:6600
	s_waitcnt vmcnt(10)
	v_add_u32_e32 v194, 52, v9
	v_cmp_gt_u32_e32 vcc, s25, v194
	v_sub_f32_e32 v196, 1.0, v166
	s_nop 0
	v_cndmask_b32_e32 v196, v166, v196, vcc
	v_mul_f32_e32 v196, v188, v196
	ds_write_b32 v10, v196 offset:6864
	s_waitcnt vmcnt(8)
	v_add_u32_e32 v194, 54, v9
	v_cmp_gt_u32_e32 vcc, s25, v194
	v_sub_f32_e32 v196, 1.0, v167
	s_nop 0
	v_cndmask_b32_e32 v196, v167, v196, vcc
	v_mul_f32_e32 v196, v189, v196
	ds_write_b32 v10, v196 offset:7128
	s_waitcnt vmcnt(6)
	v_add_u32_e32 v194, 56, v9
	v_cmp_gt_u32_e32 vcc, s25, v194
	v_sub_f32_e32 v196, 1.0, v168
	s_nop 0
	v_cndmask_b32_e32 v196, v168, v196, vcc
	v_mul_f32_e32 v196, v190, v196
	ds_write_b32 v10, v196 offset:7392
	s_waitcnt vmcnt(4)
	v_add_u32_e32 v194, 58, v9
	v_cmp_gt_u32_e32 vcc, s25, v194
	v_sub_f32_e32 v196, 1.0, v169
	s_nop 0
	v_cndmask_b32_e32 v196, v169, v196, vcc
	v_mul_f32_e32 v196, v191, v196
	ds_write_b32 v10, v196 offset:7656
	s_waitcnt vmcnt(2)
	v_add_u32_e32 v194, 60, v9
	v_cmp_gt_u32_e32 vcc, s25, v194
	v_sub_f32_e32 v196, 1.0, v170
	s_nop 0
	v_cndmask_b32_e32 v196, v170, v196, vcc
	v_mul_f32_e32 v196, v192, v196
	ds_write_b32 v10, v196 offset:7920
	s_waitcnt vmcnt(0)
	v_add_u32_e32 v194, 62, v9
	v_cmp_gt_u32_e32 vcc, s25, v194
	v_sub_f32_e32 v196, 1.0, v171
	s_nop 0
	v_cndmask_b32_e32 v196, v171, v196, vcc
	v_mul_f32_e32 v196, v193, v196
	ds_write_b32 v10, v196 offset:8184
	v_add_u32_e32 v10, 0x2100, v10
	s_waitcnt lgkmcnt(0)
	ds_read2_b32 v[6:7], v1 offset0:33 offset1:41
	ds_read2_b32 v[14:15], v1 offset1:8
	ds_read2_b32 v[20:21], v1 offset0:66 offset1:74
	ds_read2_b32 v[22:23], v1 offset0:99 offset1:107
	ds_read2_b32 v[24:25], v1 offset0:132 offset1:140
	ds_read2_b32 v[26:27], v1 offset0:165 offset1:173
	ds_read2_b32 v[28:29], v1 offset0:198 offset1:206
	ds_read2_b32 v[30:31], v1 offset0:231 offset1:239
	v_add_u32_e32 v34, s26, v18
	s_ashr_i32 s17, s16, 31
	v_ashrrev_i32_e32 v35, 31, v34
	v_lshl_add_u64 v[32:33], s[16:17], 1, v[4:5]
	v_lshlrev_b64 v[36:37], 12, v[34:35]
	s_waitcnt lgkmcnt(6)
	v_cvt_pk_bf16_f32 v10, v14, v6
	s_waitcnt lgkmcnt(4)
	v_cvt_pk_bf16_f32 v11, v20, v22
	s_waitcnt lgkmcnt(2)
	v_cvt_pk_bf16_f32 v12, v24, v26
	s_waitcnt lgkmcnt(0)
	v_cvt_pk_bf16_f32 v13, v28, v30
	v_lshl_add_u64 v[36:37], v[32:33], 0, v[36:37]
	v_add_u32_e32 v6, 8, v34
	global_store_dwordx4 v[36:37], v[10:13], off
	s_add_i32 s18, s18, s43
	s_cmpk_gt_i32 s18, 0x3ff
	v_cvt_pk_bf16_f32 v10, v15, v7
	v_ashrrev_i32_e32 v7, 31, v6
	v_cvt_pk_bf16_f32 v11, v21, v23
	v_cvt_pk_bf16_f32 v12, v25, v27
	v_cvt_pk_bf16_f32 v13, v29, v31
	v_lshlrev_b64 v[6:7], 12, v[6:7]
	ds_read2_b32 v[14:15], v1 offset0:49 offset1:57
	ds_read2_b32 v[20:21], v1 offset0:16 offset1:24
	ds_read2_b32 v[22:23], v1 offset0:82 offset1:90
	ds_read2_b32 v[24:25], v1 offset0:115 offset1:123
	ds_read2_b32 v[26:27], v1 offset0:148 offset1:156
	ds_read2_b32 v[28:29], v1 offset0:181 offset1:189
	ds_read2_b32 v[30:31], v1 offset0:214 offset1:222
	ds_read2_b32 v[36:37], v1 offset0:247 offset1:255
	v_lshl_add_u64 v[6:7], v[32:33], 0, v[6:7]
	global_store_dwordx4 v[6:7], v[10:13], off
	v_add_u32_e32 v6, 16, v34
	v_ashrrev_i32_e32 v7, 31, v6
	v_lshlrev_b64 v[6:7], 12, v[6:7]
	s_waitcnt lgkmcnt(6)
	v_cvt_pk_bf16_f32 v10, v20, v14
	s_waitcnt lgkmcnt(4)
	v_cvt_pk_bf16_f32 v11, v22, v24
	s_waitcnt lgkmcnt(2)
	v_cvt_pk_bf16_f32 v12, v26, v28
	s_waitcnt lgkmcnt(0)
	v_cvt_pk_bf16_f32 v13, v30, v36
	v_lshl_add_u64 v[6:7], v[32:33], 0, v[6:7]
	global_store_dwordx4 v[6:7], v[10:13], off
	v_add_u32_e32 v6, 24, v34
	v_ashrrev_i32_e32 v7, 31, v6
	v_lshlrev_b64 v[6:7], 12, v[6:7]
	v_cvt_pk_bf16_f32 v10, v21, v15
	v_cvt_pk_bf16_f32 v11, v23, v25
	v_cvt_pk_bf16_f32 v12, v27, v29
	v_cvt_pk_bf16_f32 v13, v31, v37
	v_lshl_add_u64 v[6:7], v[32:33], 0, v[6:7]
	global_store_dwordx4 v[6:7], v[10:13], off
	s_waitcnt lgkmcnt(0)
	s_cbranch_scc0 .LBB0_619

; template <class Fn>
; __device__ __forceinline__ void prep_mat(bf16_t* dst, int NR, int KC, int ldd, const Fn f, int& gw, int NGW, LAS float* scr, int lane) {
;     ...
; #pragma unroll 4
;         for (int i = 0; i < 32; ++i) { const int kk = 2 * i + (lane >> 5); scr[kk * 33 + (lane & 31)] = f(n0 + (lane & 31), k0 + kk); }
; __device__ __forceinline__ void prep_rwkv(const LAS unsigned* PL, int idx, bf16_t* WR2, bf16_t* WR3, bf16_t* WG, bf16_t* WO, int gw, int NGW, LAS float* scr, int lane) {
;     ...
;             prep_mat(WR2 + (size_t)2048 * 1024, 1024, 2048, 2048, [=](int n, int kk) -> float {
;                 const int k = kk & 1023, hi = kk >> 10;
;                 const float m = mu[3 * D + k];
;                 return w_v[(size_t)k * D + n] * (hi ? m : 1.f - m); }, gw, NGW, scr, lane);
.LBB0_2252:
	v_add_u32_e32 v194, 0, v9
	v_and_b32_e32 v195, 0x3ff, v194
	v_lshl_add_u32 v2, v195, 2, s24
	global_load_dword v156, v2, s[12:13]
	v_lshlrev_b32_e32 v2, 12, v195
	v_lshl_add_u64 v[198:199], v[6:7], 0, v[2:3]
	global_load_dword v172, v[198:199], off
	v_add_u32_e32 v194, 2, v9
	v_and_b32_e32 v195, 0x3ff, v194
	v_lshl_add_u32 v2, v195, 2, s24
	global_load_dword v157, v2, s[12:13]
	v_lshlrev_b32_e32 v2, 12, v195
	v_lshl_add_u64 v[198:199], v[6:7], 0, v[2:3]
	global_load_dword v173, v[198:199], off
	v_add_u32_e32 v194, 4, v9
	v_and_b32_e32 v195, 0x3ff, v194
	v_lshl_add_u32 v2, v195, 2, s24
	global_load_dword v158, v2, s[12:13]
	v_lshlrev_b32_e32 v2, 12, v195
	v_lshl_add_u64 v[198:199], v[6:7], 0, v[2:3]
	global_load_dword v174, v[198:199], off
	v_add_u32_e32 v194, 6, v9
	v_and_b32_e32 v195, 0x3ff, v194
	v_lshl_add_u32 v2, v195, 2, s24
	global_load_dword v159, v2, s[12:13]
	v_lshlrev_b32_e32 v2, 12, v195
	v_lshl_add_u64 v[198:199], v[6:7], 0, v[2:3]
	global_load_dword v175, v[198:199], off
	v_add_u32_e32 v194, 8, v9
	v_and_b32_e32 v195, 0x3ff, v194
	v_lshl_add_u32 v2, v195, 2, s24
	global_load_dword v160, v2, s[12:13]
	v_lshlrev_b32_e32 v2, 12, v195
	v_lshl_add_u64 v[198:199], v[6:7], 0, v[2:3]
	global_load_dword v182, v[198:199], off
	v_add_u32_e32 v194, 10, v9
	v_and_b32_e32 v195, 0x3ff, v194
	v_lshl_add_u32 v2, v195, 2, s24
	global_load_dword v161, v2, s[12:13]
	v_lshlrev_b32_e32 v2, 12, v195
	v_lshl_add_u64 v[198:199], v[6:7], 0, v[2:3]
	global_load_dword v183, v[198:199], off
	v_add_u32_e32 v194, 12, v9
	v_and_b32_e32 v195, 0x3ff, v194
	v_lshl_add_u32 v2, v195, 2, s24
	global_load_dword v162, v2, s[12:13]
	v_lshlrev_b32_e32 v2, 12, v195
	v_lshl_add_u64 v[198:199], v[6:7], 0, v[2:3]
	global_load_dword v184, v[198:199], off
	v_add_u32_e32 v194, 14, v9
	v_and_b32_e32 v195, 0x3ff, v194
	v_lshl_add_u32 v2, v195, 2, s24
	global_load_dword v163, v2, s[12:13]
	v_lshlrev_b32_e32 v2, 12, v195
	v_lshl_add_u64 v[198:199], v[6:7], 0, v[2:3]
	global_load_dword v185, v[198:199], off
	v_add_u32_e32 v194, 16, v9
	v_and_b32_e32 v195, 0x3ff, v194
	v_lshl_add_u32 v2, v195, 2, s24
	global_load_dword v164, v2, s[12:13]
	v_lshlrev_b32_e32 v2, 12, v195
	v_lshl_add_u64 v[198:199], v[6:7], 0, v[2:3]
	global_load_dword v186, v[198:199], off
	v_add_u32_e32 v194, 18, v9
	v_and_b32_e32 v195, 0x3ff, v194
	v_lshl_add_u32 v2, v195, 2, s24
	global_load_dword v165, v2, s[12:13]
	v_lshlrev_b32_e32 v2, 12, v195
	v_lshl_add_u64 v[198:199], v[6:7], 0, v[2:3]
	global_load_dword v187, v[198:199], off
	v_add_u32_e32 v194, 20, v9
	v_and_b32_e32 v195, 0x3ff, v194
	v_lshl_add_u32 v2, v195, 2, s24
	global_load_dword v166, v2, s[12:13]
	v_lshlrev_b32_e32 v2, 12, v195
	v_lshl_add_u64 v[198:199], v[6:7], 0, v[2:3]
	global_load_dword v188, v[198:199], off
	v_add_u32_e32 v194, 22, v9
	v_and_b32_e32 v195, 0x3ff, v194
	v_lshl_add_u32 v2, v195, 2, s24
	global_load_dword v167, v2, s[12:13]
	v_lshlrev_b32_e32 v2, 12, v195
	v_lshl_add_u64 v[198:199], v[6:7], 0, v[2:3]
	global_load_dword v189, v[198:199], off
	v_add_u32_e32 v194, 24, v9
	v_and_b32_e32 v195, 0x3ff, v194
	v_lshl_add_u32 v2, v195, 2, s24
	global_load_dword v168, v2, s[12:13]
	v_lshlrev_b32_e32 v2, 12, v195
	v_lshl_add_u64 v[198:199], v[6:7], 0, v[2:3]
	global_load_dword v190, v[198:199], off
	v_add_u32_e32 v194, 26, v9
	v_and_b32_e32 v195, 0x3ff, v194
	v_lshl_add_u32 v2, v195, 2, s24
	global_load_dword v169, v2, s[12:13]
	v_lshlrev_b32_e32 v2, 12, v195
	v_lshl_add_u64 v[198:199], v[6:7], 0, v[2:3]
	global_load_dword v191, v[198:199], off
	v_add_u32_e32 v194, 28, v9
	v_and_b32_e32 v195, 0x3ff, v194
	v_lshl_add_u32 v2, v195, 2, s24
	global_load_dword v170, v2, s[12:13]
	v_lshlrev_b32_e32 v2, 12, v195
	v_lshl_add_u64 v[198:199], v[6:7], 0, v[2:3]
	global_load_dword v192, v[198:199], off
	v_add_u32_e32 v194, 30, v9
	v_and_b32_e32 v195, 0x3ff, v194
	v_lshl_add_u32 v2, v195, 2, s24
	global_load_dword v171, v2, s[12:13]
	v_lshlrev_b32_e32 v2, 12, v195
	v_lshl_add_u64 v[198:199], v[6:7], 0, v[2:3]
	global_load_dword v193, v[198:199], off
	s_waitcnt vmcnt(30)
	v_add_u32_e32 v194, 0, v9
	v_cmp_gt_u32_e32 vcc, s25, v194
	v_sub_f32_e32 v196, 1.0, v156
	s_nop 0
	v_cndmask_b32_e32 v196, v156, v196, vcc
	v_mul_f32_e32 v196, v172, v196
	ds_write_b32 v10, v196
	s_waitcnt vmcnt(28)
	v_add_u32_e32 v194, 2, v9
	v_cmp_gt_u32_e32 vcc, s25, v194
	v_sub_f32_e32 v196, 1.0, v157
	s_nop 0
	v_cndmask_b32_e32 v196, v157, v196, vcc
	v_mul_f32_e32 v196, v173, v196
	ds_write_b32 v10, v196 offset:264
	s_waitcnt vmcnt(26)
	v_add_u32_e32 v194, 4, v9
	v_cmp_gt_u32_e32 vcc, s25, v194
	v_sub_f32_e32 v196, 1.0, v158
	s_nop 0
	v_cndmask_b32_e32 v196, v158, v196, vcc
	v_mul_f32_e32 v196, v174, v196
	ds_write_b32 v10, v196 offset:528
	s_waitcnt vmcnt(24)
	v_add_u32_e32 v194, 6, v9
	v_cmp_gt_u32_e32 vcc, s25, v194
	v_sub_f32_e32 v196, 1.0, v159
	s_nop 0
	v_cndmask_b32_e32 v196, v159, v196, vcc
	v_mul_f32_e32 v196, v175, v196
	ds_write_b32 v10, v196 offset:792
	s_waitcnt vmcnt(22)
	v_add_u32_e32 v194, 8, v9
	v_cmp_gt_u32_e32 vcc, s25, v194
	v_sub_f32_e32 v196, 1.0, v160
	s_nop 0
	v_cndmask_b32_e32 v196, v160, v196, vcc
	v_mul_f32_e32 v196, v182, v196
	ds_write_b32 v10, v196 offset:1056
	s_waitcnt vmcnt(20)
	v_add_u32_e32 v194, 10, v9
	v_cmp_gt_u32_e32 vcc, s25, v194
	v_sub_f32_e32 v196, 1.0, v161
	s_nop 0
	v_cndmask_b32_e32 v196, v161, v196, vcc
	v_mul_f32_e32 v196, v183, v196
	ds_write_b32 v10, v196 offset:1320
	s_waitcnt vmcnt(18)
	v_add_u32_e32 v194, 12, v9
	v_cmp_gt_u32_e32 vcc, s25, v194
	v_sub_f32_e32 v196, 1.0, v162
	s_nop 0
	v_cndmask_b32_e32 v196, v162, v196, vcc
	v_mul_f32_e32 v196, v184, v196
	ds_write_b32 v10, v196 offset:1584
	s_waitcnt vmcnt(16)
; template <class Fn>
; __device__ __forceinline__ void prep_mat(bf16_t* dst, int NR, int KC, int ldd, const Fn f, int& gw, int NGW, LAS float* scr, int lane) {
;     ...
; #pragma unroll 4
;         for (int i = 0; i < 32; ++i) { const int kk = 2 * i + (lane >> 5); scr[kk * 33 + (lane & 31)] = f(n0 + (lane & 31), k0 + kk); }
; __device__ __forceinline__ void prep_rwkv(const LAS unsigned* PL, int idx, bf16_t* WR2, bf16_t* WR3, bf16_t* WG, bf16_t* WO, int gw, int NGW, LAS float* scr, int lane) {
;     ...
;             prep_mat(WR2 + (size_t)2048 * 1024, 1024, 2048, 2048, [=](int n, int kk) -> float {
;                 const int k = kk & 1023, hi = kk >> 10;
;                 const float m = mu[3 * D + k];
;                 return w_v[(size_t)k * D + n] * (hi ? m : 1.f - m); }, gw, NGW, scr, lane);
	v_add_u32_e32 v194, 14, v9
	v_cmp_gt_u32_e32 vcc, s25, v194
	v_sub_f32_e32 v196, 1.0, v163
	s_nop 0
	v_cndmask_b32_e32 v196, v163, v196, vcc
	v_mul_f32_e32 v196, v185, v196
	ds_write_b32 v10, v196 offset:1848
	s_waitcnt vmcnt(14)
	v_add_u32_e32 v194, 16, v9
	v_cmp_gt_u32_e32 vcc, s25, v194
	v_sub_f32_e32 v196, 1.0, v164
	s_nop 0
	v_cndmask_b32_e32 v196, v164, v196, vcc
	v_mul_f32_e32 v196, v186, v196
	ds_write_b32 v10, v196 offset:2112
	s_waitcnt vmcnt(12)
	v_add_u32_e32 v194, 18, v9
	v_cmp_gt_u32_e32 vcc, s25, v194
	v_sub_f32_e32 v196, 1.0, v165
	s_nop 0
	v_cndmask_b32_e32 v196, v165, v196, vcc
	v_mul_f32_e32 v196, v187, v196
	ds_write_b32 v10, v196 offset:2376
	s_waitcnt vmcnt(10)
	v_add_u32_e32 v194, 20, v9
	v_cmp_gt_u32_e32 vcc, s25, v194
	v_sub_f32_e32 v196, 1.0, v166
	s_nop 0
	v_cndmask_b32_e32 v196, v166, v196, vcc
	v_mul_f32_e32 v196, v188, v196
	ds_write_b32 v10, v196 offset:2640
	s_waitcnt vmcnt(8)
	v_add_u32_e32 v194, 22, v9
	v_cmp_gt_u32_e32 vcc, s25, v194
	v_sub_f32_e32 v196, 1.0, v167
	s_nop 0
	v_cndmask_b32_e32 v196, v167, v196, vcc
	v_mul_f32_e32 v196, v189, v196
	ds_write_b32 v10, v196 offset:2904
	s_waitcnt vmcnt(6)
	v_add_u32_e32 v194, 24, v9
	v_cmp_gt_u32_e32 vcc, s25, v194
	v_sub_f32_e32 v196, 1.0, v168
	s_nop 0
	v_cndmask_b32_e32 v196, v168, v196, vcc
	v_mul_f32_e32 v196, v190, v196
	ds_write_b32 v10, v196 offset:3168
	s_waitcnt vmcnt(4)
	v_add_u32_e32 v194, 26, v9
	v_cmp_gt_u32_e32 vcc, s25, v194
	v_sub_f32_e32 v196, 1.0, v169
	s_nop 0
	v_cndmask_b32_e32 v196, v169, v196, vcc
	v_mul_f32_e32 v196, v191, v196
	ds_write_b32 v10, v196 offset:3432
	s_waitcnt vmcnt(2)
	v_add_u32_e32 v194, 28, v9
	v_cmp_gt_u32_e32 vcc, s25, v194
	v_sub_f32_e32 v196, 1.0, v170
	s_nop 0
	v_cndmask_b32_e32 v196, v170, v196, vcc
	v_mul_f32_e32 v196, v192, v196
	ds_write_b32 v10, v196 offset:3696
	s_waitcnt vmcnt(0)
	v_add_u32_e32 v194, 30, v9
	v_cmp_gt_u32_e32 vcc, s25, v194
	v_sub_f32_e32 v196, 1.0, v171
	s_nop 0
	v_cndmask_b32_e32 v196, v171, v196, vcc
	v_mul_f32_e32 v196, v193, v196
	ds_write_b32 v10, v196 offset:3960
	v_add_u32_e32 v194, 32, v9
	v_and_b32_e32 v195, 0x3ff, v194
	v_lshl_add_u32 v2, v195, 2, s24
	global_load_dword v156, v2, s[12:13]
	v_lshlrev_b32_e32 v2, 12, v195
	v_lshl_add_u64 v[198:199], v[6:7], 0, v[2:3]
	global_load_dword v172, v[198:199], off
	v_add_u32_e32 v194, 34, v9
	v_and_b32_e32 v195, 0x3ff, v194
	v_lshl_add_u32 v2, v195, 2, s24
	global_load_dword v157, v2, s[12:13]
	v_lshlrev_b32_e32 v2, 12, v195
	v_lshl_add_u64 v[198:199], v[6:7], 0, v[2:3]
	global_load_dword v173, v[198:199], off
	v_add_u32_e32 v194, 36, v9
	v_and_b32_e32 v195, 0x3ff, v194
	v_lshl_add_u32 v2, v195, 2, s24
	global_load_dword v158, v2, s[12:13]
	v_lshlrev_b32_e32 v2, 12, v195
	v_lshl_add_u64 v[198:199], v[6:7], 0, v[2:3]
	global_load_dword v174, v[198:199], off
	v_add_u32_e32 v194, 38, v9
	v_and_b32_e32 v195, 0x3ff, v194
	v_lshl_add_u32 v2, v195, 2, s24
	global_load_dword v159, v2, s[12:13]
	v_lshlrev_b32_e32 v2, 12, v195
	v_lshl_add_u64 v[198:199], v[6:7], 0, v[2:3]
	global_load_dword v175, v[198:199], off
	v_add_u32_e32 v194, 40, v9
	v_and_b32_e32 v195, 0x3ff, v194
	v_lshl_add_u32 v2, v195, 2, s24
	global_load_dword v160, v2, s[12:13]
	v_lshlrev_b32_e32 v2, 12, v195
	v_lshl_add_u64 v[198:199], v[6:7], 0, v[2:3]
	global_load_dword v182, v[198:199], off
	v_add_u32_e32 v194, 42, v9
	v_and_b32_e32 v195, 0x3ff, v194
	v_lshl_add_u32 v2, v195, 2, s24
	global_load_dword v161, v2, s[12:13]
	v_lshlrev_b32_e32 v2, 12, v195
	v_lshl_add_u64 v[198:199], v[6:7], 0, v[2:3]
	global_load_dword v183, v[198:199], off
	v_add_u32_e32 v194, 44, v9
	v_and_b32_e32 v195, 0x3ff, v194
	v_lshl_add_u32 v2, v195, 2, s24
	global_load_dword v162, v2, s[12:13]
	v_lshlrev_b32_e32 v2, 12, v195
	v_lshl_add_u64 v[198:199], v[6:7], 0, v[2:3]
	global_load_dword v184, v[198:199], off
	v_add_u32_e32 v194, 46, v9
	v_and_b32_e32 v195, 0x3ff, v194
	v_lshl_add_u32 v2, v195, 2, s24
	global_load_dword v163, v2, s[12:13]
	v_lshlrev_b32_e32 v2, 12, v195
	v_lshl_add_u64 v[198:199], v[6:7], 0, v[2:3]
	global_load_dword v185, v[198:199], off
	v_add_u32_e32 v194, 48, v9
	v_and_b32_e32 v195, 0x3ff, v194
	v_lshl_add_u32 v2, v195, 2, s24
	global_load_dword v164, v2, s[12:13]
	v_lshlrev_b32_e32 v2, 12, v195
	v_lshl_add_u64 v[198:199], v[6:7], 0, v[2:3]
	global_load_dword v186, v[198:199], off
	v_add_u32_e32 v194, 50, v9
	v_and_b32_e32 v195, 0x3ff, v194
	v_lshl_add_u32 v2, v195, 2, s24
	global_load_dword v165, v2, s[12:13]
	v_lshlrev_b32_e32 v2, 12, v195
	v_lshl_add_u64 v[198:199], v[6:7], 0, v[2:3]
	global_load_dword v187, v[198:199], off
	v_add_u32_e32 v194, 52, v9
	v_and_b32_e32 v195, 0x3ff, v194
	v_lshl_add_u32 v2, v195, 2, s24
	global_load_dword v166, v2, s[12:13]
	v_lshlrev_b32_e32 v2, 12, v195
	v_lshl_add_u64 v[198:199], v[6:7], 0, v[2:3]
	global_load_dword v188, v[198:199], off
	v_add_u32_e32 v194, 54, v9
	v_and_b32_e32 v195, 0x3ff, v194
	v_lshl_add_u32 v2, v195, 2, s24
	global_load_dword v167, v2, s[12:13]
	v_lshlrev_b32_e32 v2, 12, v195
	v_lshl_add_u64 v[198:199], v[6:7], 0, v[2:3]
	global_load_dword v189, v[198:199], off
	v_add_u32_e32 v194, 56, v9
	v_and_b32_e32 v195, 0x3ff, v194
	v_lshl_add_u32 v2, v195, 2, s24
	global_load_dword v168, v2, s[12:13]
	v_lshlrev_b32_e32 v2, 12, v195
	v_lshl_add_u64 v[198:199], v[6:7], 0, v[2:3]
	global_load_dword v190, v[198:199], off
	v_add_u32_e32 v194, 58, v9
	v_and_b32_e32 v195, 0x3ff, v194
	v_lshl_add_u32 v2, v195, 2, s24
	global_load_dword v169, v2, s[12:13]
	v_lshlrev_b32_e32 v2, 12, v195
	v_lshl_add_u64 v[198:199], v[6:7], 0, v[2:3]
	global_load_dword v191, v[198:199], off
	v_add_u32_e32 v194, 60, v9
	v_and_b32_e32 v195, 0x3ff, v194
	v_lshl_add_u32 v2, v195, 2, s24
	global_load_dword v170, v2, s[12:13]
	v_lshlrev_b32_e32 v2, 12, v195
	v_lshl_add_u64 v[198:199], v[6:7], 0, v[2:3]
	global_load_dword v192, v[198:199], off
	v_add_u32_e32 v194, 62, v9
	v_and_b32_e32 v195, 0x3ff, v194
	v_lshl_add_u32 v2, v195, 2, s24
	global_load_dword v171, v2, s[12:13]
	v_lshlrev_b32_e32 v2, 12, v195
	v_lshl_add_u64 v[198:199], v[6:7], 0, v[2:3]
	global_load_dword v193, v[198:199], off
	s_waitcnt vmcnt(30)
; #define LAS __attribute__((address_space(3)))
; #define GAS __attribute__((address_space(1)))
; __device__ __forceinline__ unsigned cvt_pk_bf16(float lo, float hi) { const f32x2 v = {lo, hi}; return __builtin_bit_cast(unsigned, __builtin_convertvector(v, b16x2_t)); }
; #define LDS_WAIT() asm volatile("s_waitcnt lgkmcnt(0)" ::: "memory")
; template <class Fn>
; __device__ __forceinline__ void prep_mat(bf16_t* dst, int NR, int KC, int ldd, const Fn f, int& gw, int NGW, LAS float* scr, int lane) {
;     ...
; #pragma unroll 4
;         for (int i = 0; i < 32; ++i) { const int kk = 2 * i + (lane >> 5); scr[kk * 33 + (lane & 31)] = f(n0 + (lane & 31), k0 + kk); }
;         LDS_WAIT(); asm volatile("" ::: "memory");
;         const int c = lane & 7;
; #pragma unroll
;         for (int j = 0; j < 4; ++j) { const int n = (lane >> 3) + 8 * j; const LAS float* s = scr + (8 * c) * 33 + n;
;             u32x4 o; o.x = cvt_pk_bf16(s[0 * 33], s[1 * 33]); o.y = cvt_pk_bf16(s[2 * 33], s[3 * 33]); o.z = cvt_pk_bf16(s[4 * 33], s[5 * 33]); o.w = cvt_pk_bf16(s[6 * 33], s[7 * 33]);
;             *(GAS u32x4*)(dst + (size_t)(n0 + n) * ldd + k0 + 8 * c) = o; }
;         LDS_WAIT(); asm volatile("" ::: "memory");
;     }
; __device__ __forceinline__ void prep_rwkv(const LAS unsigned* PL, int idx, bf16_t* WR2, bf16_t* WR3, bf16_t* WG, bf16_t* WO, int gw, int NGW, LAS float* scr, int lane) {
;     ...
;             prep_mat(WR2 + (size_t)2048 * 1024, 1024, 2048, 2048, [=](int n, int kk) -> float {
;                 const int k = kk & 1023, hi = kk >> 10;
;                 const float m = mu[3 * D + k];
;                 return w_v[(size_t)k * D + n] * (hi ? m : 1.f - m); }, gw, NGW, scr, lane);
	v_add_u32_e32 v194, 32, v9
	v_cmp_gt_u32_e32 vcc, s25, v194
	v_sub_f32_e32 v196, 1.0, v156
	s_nop 0
	v_cndmask_b32_e32 v196, v156, v196, vcc
	v_mul_f32_e32 v196, v172, v196
	ds_write_b32 v10, v196 offset:4224
	s_waitcnt vmcnt(28)
	v_add_u32_e32 v194, 34, v9
	v_cmp_gt_u32_e32 vcc, s25, v194
	v_sub_f32_e32 v196, 1.0, v157
	s_nop 0
	v_cndmask_b32_e32 v196, v157, v196, vcc
	v_mul_f32_e32 v196, v173, v196
	ds_write_b32 v10, v196 offset:4488
	s_waitcnt vmcnt(26)
	v_add_u32_e32 v194, 36, v9
	v_cmp_gt_u32_e32 vcc, s25, v194
	v_sub_f32_e32 v196, 1.0, v158
	s_nop 0
	v_cndmask_b32_e32 v196, v158, v196, vcc
	v_mul_f32_e32 v196, v174, v196
	ds_write_b32 v10, v196 offset:4752
	s_waitcnt vmcnt(24)
	v_add_u32_e32 v194, 38, v9
	v_cmp_gt_u32_e32 vcc, s25, v194
	v_sub_f32_e32 v196, 1.0, v159
	s_nop 0
	v_cndmask_b32_e32 v196, v159, v196, vcc
	v_mul_f32_e32 v196, v175, v196
	ds_write_b32 v10, v196 offset:5016
	s_waitcnt vmcnt(22)
	v_add_u32_e32 v194, 40, v9
	v_cmp_gt_u32_e32 vcc, s25, v194
	v_sub_f32_e32 v196, 1.0, v160
	s_nop 0
	v_cndmask_b32_e32 v196, v160, v196, vcc
	v_mul_f32_e32 v196, v182, v196
	ds_write_b32 v10, v196 offset:5280
	s_waitcnt vmcnt(20)
	v_add_u32_e32 v194, 42, v9
	v_cmp_gt_u32_e32 vcc, s25, v194
	v_sub_f32_e32 v196, 1.0, v161
	s_nop 0
	v_cndmask_b32_e32 v196, v161, v196, vcc
	v_mul_f32_e32 v196, v183, v196
	ds_write_b32 v10, v196 offset:5544
	s_waitcnt vmcnt(18)
	v_add_u32_e32 v194, 44, v9
	v_cmp_gt_u32_e32 vcc, s25, v194
	v_sub_f32_e32 v196, 1.0, v162
	s_nop 0
	v_cndmask_b32_e32 v196, v162, v196, vcc
	v_mul_f32_e32 v196, v184, v196
	ds_write_b32 v10, v196 offset:5808
	s_waitcnt vmcnt(16)
	v_add_u32_e32 v194, 46, v9
	v_cmp_gt_u32_e32 vcc, s25, v194
	v_sub_f32_e32 v196, 1.0, v163
	s_nop 0
	v_cndmask_b32_e32 v196, v163, v196, vcc
	v_mul_f32_e32 v196, v185, v196
	ds_write_b32 v10, v196 offset:6072
	s_waitcnt vmcnt(14)
	v_add_u32_e32 v194, 48, v9
	v_cmp_gt_u32_e32 vcc, s25, v194
	v_sub_f32_e32 v196, 1.0, v164
	s_nop 0
	v_cndmask_b32_e32 v196, v164, v196, vcc
	v_mul_f32_e32 v196, v186, v196
	ds_write_b32 v10, v196 offset:6336
	s_waitcnt vmcnt(12)
	v_add_u32_e32 v194, 50, v9
	v_cmp_gt_u32_e32 vcc, s25, v194
	v_sub_f32_e32 v196, 1.0, v165
	s_nop 0
	v_cndmask_b32_e32 v196, v165, v196, vcc
	v_mul_f32_e32 v196, v187, v196
	ds_write_b32 v10, v196 offset:6600
	s_waitcnt vmcnt(10)
	v_add_u32_e32 v194, 52, v9
	v_cmp_gt_u32_e32 vcc, s25, v194
	v_sub_f32_e32 v196, 1.0, v166
	s_nop 0
	v_cndmask_b32_e32 v196, v166, v196, vcc
	v_mul_f32_e32 v196, v188, v196
	ds_write_b32 v10, v196 offset:6864
	s_waitcnt vmcnt(8)
	v_add_u32_e32 v194, 54, v9
	v_cmp_gt_u32_e32 vcc, s25, v194
	v_sub_f32_e32 v196, 1.0, v167
	s_nop 0
	v_cndmask_b32_e32 v196, v167, v196, vcc
	v_mul_f32_e32 v196, v189, v196
	ds_write_b32 v10, v196 offset:7128
	s_waitcnt vmcnt(6)
	v_add_u32_e32 v194, 56, v9
	v_cmp_gt_u32_e32 vcc, s25, v194
	v_sub_f32_e32 v196, 1.0, v168
	s_nop 0
	v_cndmask_b32_e32 v196, v168, v196, vcc
	v_mul_f32_e32 v196, v190, v196
	ds_write_b32 v10, v196 offset:7392
	s_waitcnt vmcnt(4)
	v_add_u32_e32 v194, 58, v9
	v_cmp_gt_u32_e32 vcc, s25, v194
	v_sub_f32_e32 v196, 1.0, v169
	s_nop 0
	v_cndmask_b32_e32 v196, v169, v196, vcc
	v_mul_f32_e32 v196, v191, v196
	ds_write_b32 v10, v196 offset:7656
	s_waitcnt vmcnt(2)
	v_add_u32_e32 v194, 60, v9
	v_cmp_gt_u32_e32 vcc, s25, v194
	v_sub_f32_e32 v196, 1.0, v170
	s_nop 0
	v_cndmask_b32_e32 v196, v170, v196, vcc
	v_mul_f32_e32 v196, v192, v196
	ds_write_b32 v10, v196 offset:7920
	s_waitcnt vmcnt(0)
	v_add_u32_e32 v194, 62, v9
	v_cmp_gt_u32_e32 vcc, s25, v194
	v_sub_f32_e32 v196, 1.0, v171
	s_nop 0
	v_cndmask_b32_e32 v196, v171, v196, vcc
	v_mul_f32_e32 v196, v193, v196
	ds_write_b32 v10, v196 offset:8184
	v_add_u32_e32 v10, 0x2100, v10
	s_waitcnt lgkmcnt(0)
	ds_read2_b32 v[6:7], v1 offset0:33 offset1:41
	ds_read2_b32 v[14:15], v1 offset1:8
	ds_read2_b32 v[20:21], v1 offset0:66 offset1:74
	ds_read2_b32 v[22:23], v1 offset0:99 offset1:107
	ds_read2_b32 v[24:25], v1 offset0:132 offset1:140
	ds_read2_b32 v[26:27], v1 offset0:165 offset1:173
	ds_read2_b32 v[28:29], v1 offset0:198 offset1:206
	ds_read2_b32 v[30:31], v1 offset0:231 offset1:239
	v_add_u32_e32 v34, s26, v18
	s_ashr_i32 s17, s16, 31
	v_ashrrev_i32_e32 v35, 31, v34
	v_lshl_add_u64 v[32:33], s[16:17], 1, v[4:5]
	v_lshlrev_b64 v[36:37], 12, v[34:35]
	s_waitcnt lgkmcnt(6)
	v_cvt_pk_bf16_f32 v10, v14, v6
	s_waitcnt lgkmcnt(4)
	v_cvt_pk_bf16_f32 v11, v20, v22
	s_waitcnt lgkmcnt(2)
	v_cvt_pk_bf16_f32 v12, v24, v26
	s_waitcnt lgkmcnt(0)
	v_cvt_pk_bf16_f32 v13, v28, v30
	v_lshl_add_u64 v[36:37], v[32:33], 0, v[36:37]
	v_add_u32_e32 v6, 8, v34
	global_store_dwordx4 v[36:37], v[10:13], off
	s_add_i32 s19, s19, s49
	s_cmpk_gt_i32 s19, 0x3ff
	v_cvt_pk_bf16_f32 v10, v15, v7
	v_ashrrev_i32_e32 v7, 31, v6
	v_cvt_pk_bf16_f32 v11, v21, v23
	v_cvt_pk_bf16_f32 v12, v25, v27
	v_cvt_pk_bf16_f32 v13, v29, v31
	v_lshlrev_b64 v[6:7], 12, v[6:7]
	ds_read2_b32 v[14:15], v1 offset0:49 offset1:57
	ds_read2_b32 v[20:21], v1 offset0:16 offset1:24
	ds_read2_b32 v[22:23], v1 offset0:82 offset1:90
	ds_read2_b32 v[24:25], v1 offset0:115 offset1:123
	ds_read2_b32 v[26:27], v1 offset0:148 offset1:156
	ds_read2_b32 v[28:29], v1 offset0:181 offset1:189
	ds_read2_b32 v[30:31], v1 offset0:214 offset1:222
	ds_read2_b32 v[36:37], v1 offset0:247 offset1:255
	v_lshl_add_u64 v[6:7], v[32:33], 0, v[6:7]
	global_store_dwordx4 v[6:7], v[10:13], off
	v_add_u32_e32 v6, 16, v34
	v_ashrrev_i32_e32 v7, 31, v6
	v_lshlrev_b64 v[6:7], 12, v[6:7]
	s_waitcnt lgkmcnt(6)
	v_cvt_pk_bf16_f32 v10, v20, v14
	s_waitcnt lgkmcnt(4)
	v_cvt_pk_bf16_f32 v11, v22, v24
	s_waitcnt lgkmcnt(2)
	v_cvt_pk_bf16_f32 v12, v26, v28
	s_waitcnt lgkmcnt(0)
	v_cvt_pk_bf16_f32 v13, v30, v36
	v_lshl_add_u64 v[6:7], v[32:33], 0, v[6:7]
	global_store_dwordx4 v[6:7], v[10:13], off
	v_add_u32_e32 v6, 24, v34
	v_ashrrev_i32_e32 v7, 31, v6
	v_lshlrev_b64 v[6:7], 12, v[6:7]
	v_cvt_pk_bf16_f32 v10, v21, v15
	v_cvt_pk_bf16_f32 v11, v23, v25
	v_cvt_pk_bf16_f32 v12, v27, v29
	v_cvt_pk_bf16_f32 v13, v31, v37
	v_lshl_add_u64 v[6:7], v[32:33], 0, v[6:7]
	global_store_dwordx4 v[6:7], v[10:13], off
	s_waitcnt lgkmcnt(0)
	s_cbranch_scc0 .LBB0_2251
